# no grid barrier between final-norm phase and next group's row prep (no cross-workgroup dependency) on top of 16x16x32 MFMA GEMM loops
# speedup vs baseline: 1.0176x; 1.0034x over previous
; __device__ void run_phase(CP& p, int ph, char* lds) {
;     ...
;   if (ph <= NMETA_PH) { g = -1; k = ph - 1; }
;   else { g = (ph - 1 - NMETA_PH) / PH_PER_G; k = (ph - 1 - NMETA_PH) - g * PH_PER_G; }
; __global__ void __launch_bounds__(256, 2) mega(Params p, int ph_lo, int ph_hi, int coop) {
;     ...
;   for (int ph = ph_lo; ph < ph_hi; ++ph) {
;     run_phase(*pp, ph, lds);
;     if (coop && ph + 1 < ph_hi) {
;       if (ph == 0) cg::this_grid().sync();
;       else xcd_barrier(xb);
;     }
.LBB0_946:
	s_add_i32 s60, s60, 1
	s_cmp_ge_i32 s60, s61
	s_waitcnt lgkmcnt(0)
	s_cselect_b64 s[26:27], -1, 0
	s_cmp_lt_i32 s60, s61
	v_readlane_b32 s6, v253, 17
	s_cselect_b64 s[0:1], -1, 0
	v_readlane_b32 s7, v253, 18
	s_and_b64 s[0:1], s[6:7], s[0:1]
	s_add_i32 s98, s60, -6
	s_mul_hi_u32 s99, s98, 0x4ec4ec4f
	s_lshr_b32 s99, s99, 2
	s_mul_i32 s99, s99, -13
	s_add_i32 s99, s99, s98
	s_cmp_lt_i32 s98, 0
	s_cselect_b32 s99, 0, s99
	s_cmp_eq_u32 s99, 12
	s_cselect_b64 s[98:99], 0, -1
	s_and_b64 s[0:1], s[0:1], s[98:99]
	s_andn2_b64 vcc, exec, s[0:1]
	s_cbranch_vccz .LBB0_947
	s_getpc_b64 s[98:99]
